# v20 + static s_setprio 1 for waves 4-7 during the dense (MLA) attention phase
# speedup vs baseline: 1.0061x; 1.0061x over previous
.LBB0_1471:
	s_and_b32 s14, s14, 0x3fffffc0
	s_lshl_b32 s14, s14, 2
	s_lshl_b32 s12, s22, 5
	s_add_i32 s42, s14, 0
	s_cmp_lg_u32 0, -1
	s_cselect_b32 s14, 0, 0
	s_add_i32 s14, s14, s15
	s_add_i32 s43, s14, 0x6000
	s_mul_i32 s14, s22, 0x1800
	s_add_i32 s14, s14, 0
	s_add_i32 s24, s14, 0x12800
	s_lshl_b64 s[14:15], s[8:9], 11
	s_lshl_b32 s8, s29, 8
	s_and_b32 s48, s8, 0x700
	s_lshl_b64 s[8:9], s[18:19], 1
	s_add_u32 s8, s34, s8
	s_addc_u32 s9, s35, s9
	s_lshl_b32 s18, s0, 1
	s_add_u32 s8, s8, s18
	s_addc_u32 s9, s9, 0
	s_or_b32 s25, s14, s48
	s_mulk_i32 s13, 0xc0
	s_add_u32 s18, s30, s13
	v_lshlrev_b32_e32 v7, 3, v7
	s_addc_u32 s19, s31, 0
	v_or_b32_e32 v8, v8, v7
	s_and_b64 s[6:7], s[6:7], exec
	v_lshlrev_b32_e32 v181, 1, v8
	s_cselect_b32 s44, 4, 0
	s_ashr_i32 s13, s12, 31
	v_or_b32_e32 v8, s25, v5
	v_mov_b32_e32 v9, s15
	v_lshl_add_u64 v[8:9], v[8:9], 0, s[12:13]
	s_movk_i32 s45, 0x600
	v_mov_b64_e32 v[10:11], s[18:19]
	v_mad_u64_u32 v[10:11], s[6:7], v8, s45, v[10:11]
	v_mad_i32_i24 v11, v9, s45, v11
	v_mov_b32_e32 v167, 0
	v_lshlrev_b32_e32 v166, 1, v2
	s_movk_i32 s23, 0x6000
	v_lshl_add_u64 v[8:9], v[10:11], 0, v[166:167]
	s_nop 4
	s_mov_b32 s6, m0
	s_mov_b32 m0, s43
	s_nop 0
	global_load_lds_dwordx4 v181, s[8:9]
	s_mov_b32 m0, s6
	v_add_co_u32_e32 v10, vcc, s23, v8
	v_lshlrev_b32_e32 v6, 5, v6
	s_nop 0
	v_addc_co_u32_e32 v11, vcc, 0, v9, vcc
	global_load_dwordx4 v[98:101], v[8:9], off
	global_load_dwordx4 v[102:105], v[8:9], off offset:64
	global_load_dwordx4 v[106:109], v[10:11], off
	global_load_dwordx4 v[110:113], v[8:9], off offset:128
	global_load_dwordx4 v[114:117], v[10:11], off offset:64
	global_load_dwordx4 v[118:121], v[10:11], off offset:128
	v_lshrrev_b32_e32 v9, 5, v4
	v_and_b32_e32 v6, 32, v6
	v_lshlrev_b32_e32 v12, 4, v3
	v_add3_u32 v6, 0, v6, v7
	v_lshlrev_b32_e32 v7, 8, v9
	v_and_b32_e32 v12, 0xc0, v12
	v_add3_u32 v183, v6, v7, v12
	v_lshrrev_b32_e32 v6, 2, v3
	v_and_b32_e32 v8, 31, v3
	v_bitop3_b32 v6, v9, v6, 3 bitop3:0x78
	s_lshl_b32 s8, s22, 12
	v_lshlrev_b32_e32 v10, 6, v3
	v_lshlrev_b32_e32 v184, 4, v6
	v_or_b32_e32 v168, s12, v5
	s_add_i32 s8, s8, 0
	v_lshlrev_b32_e32 v5, 9, v9
	v_lshlrev_b32_e32 v6, 1, v8
	v_and_b32_e32 v11, 0x400, v10
	v_and_b32_e32 v10, 0x3c0, v10
	v_add3_u32 v188, s8, v5, v6
	v_lshrrev_b32_e32 v5, 3, v4
	v_lshlrev_b32_e32 v3, 3, v3
	v_add3_u32 v182, 0, v11, v10
	v_lshlrev_b32_e32 v7, 4, v4
	v_add3_u32 v185, s24, v11, v10
	v_cmp_gt_u32_e64 s[6:7], 32, v4
	v_lshl_add_u32 v186, v8, 2, s42
	v_lshlrev_b32_e32 v187, 4, v9
	v_and_b32_e32 v4, 56, v3
	v_lshlrev_b32_e32 v9, 7, v5
	v_lshlrev_b32_e32 v6, 10, v5
	v_or_b32_e32 v8, 8, v5
	v_or_b32_e32 v10, 16, v5
	v_or_b32_e32 v5, 24, v5
	v_mov_b32_e32 v169, s13
	v_lshl_add_u32 v3, v4, 1, s8
	v_lshlrev_b32_e32 v11, 7, v8
	v_lshlrev_b32_e32 v8, 10, v8
	v_lshlrev_b32_e32 v13, 7, v10
	v_lshlrev_b32_e32 v10, 10, v10
	v_lshlrev_b32_e32 v14, 7, v5
	v_lshlrev_b32_e32 v12, 10, v5
	s_add_u32 s13, s16, 0x2000
	v_lshlrev_b32_e32 v170, 1, v2
	v_bfrev_b32_e32 v2, 1
	v_xor_b32_e32 v189, 32, v184
	s_addc_u32 s46, s17, 0
	v_add_u32_e32 v190, s24, v7
	s_mov_b32 s47, 0x41000000
	v_lshlrev_b32_e32 v166, 1, v4
	v_add_u32_e32 v191, v3, v9
	v_lshlrev_b32_e32 v172, 1, v6
	v_add_u32_e32 v192, v3, v11
	v_lshlrev_b32_e32 v174, 1, v8
	v_add_u32_e32 v193, v3, v13
	v_lshlrev_b32_e32 v176, 1, v10
	s_waitcnt lgkmcnt(0)
	v_add_u32_e32 v194, v3, v14
	v_lshlrev_b32_e32 v178, 1, v12
	v_mov_b32_e32 v3, v2
	v_mov_b32_e32 v4, v2
	v_mov_b32_e32 v5, v2
	v_mov_b32_e32 v6, v2
	v_mov_b32_e32 v7, v2
	v_mov_b32_e32 v8, v2
	v_mov_b32_e32 v9, v2
	v_mov_b32_e32 v10, v2
	v_mov_b32_e32 v11, v2
	v_mov_b32_e32 v12, v2
	v_mov_b32_e32 v13, v2
	v_mov_b32_e32 v14, v2
	v_mov_b32_e32 v15, v2
	v_mov_b32_e32 v16, v2
	v_mov_b32_e32 v17, v2
	s_mov_b32 s49, s1
	s_mov_b32 s50, s1
	s_cmp_lt_i32 s22, 4
	s_cbranch_scc1 .Lmla_noprio
	s_setprio 1

.LBB0_1496:
	s_waitcnt vmcnt(0) lgkmcnt(0)
	s_barrier
	s_setprio 0
